# gMLP item: all global loads batched (ss partials, 20 staging loads, 20 epilogue loads prefetched), stores left in flight; dtype comment added
# baseline (speedup 1.0000x reference)
.LBB0_377:
	s_or_b64 exec, exec, s[22:23]
	s_lshl_b64 s[22:23], s[6:7], 2
	s_add_u32 s9, s26, s22
	s_addc_u32 s25, s27, s23
	s_and_b32 s2, s0, 3
	s_lshl_b32 s3, s2, 9
	s_add_u32 s26, s9, s3
	s_addc_u32 s27, s25, 0
	s_ashr_i32 s25, s24, 31
	s_lshl_b64 s[24:25], s[24:25], 17
	s_add_u32 s9, s12, s24
	s_addc_u32 s25, s13, s25
	s_lshl_b32 s31, s2, 15
	s_add_u32 s24, s9, s31
	s_addc_u32 s25, s25, 0
	v_lshlrev_b32_e32 v1, 3, v0
	v_ashrrev_i32_e32 v22, 3, v0
	s_add_u32 s34, s12, s31
	v_and_b32_e32 v4, 56, v1
	s_addc_u32 s35, s13, 0
	v_lshlrev_b32_e32 v144, 1, v4
	v_lshrrev_b32_e32 v1, 1, v22
	v_lshl_add_u64 v[2:3], s[34:35], 0, v[144:145]
	s_mov_b64 s[34:35], 0x39c0000
	v_xor_b32_e32 v0, v1, v0
	v_ashrrev_i32_e32 v23, 31, v22
	v_lshl_add_u64 v[26:27], v[2:3], 0, s[34:35]
	v_lshlrev_b32_e32 v0, 4, v0
	v_lshlrev_b64 v[8:9], 8, v[22:23]
	v_and_b32_e32 v34, 0x70, v0
	v_lshl_add_u64 v[0:1], s[24:25], 0, v[144:145]
	v_lshl_add_u32 v31, v4, 2, s28
	v_lshl_add_u64 v[10:11], v[26:27], 0, v[8:9]
	s_waitcnt lgkmcnt(0)
	s_barrier
	v_lshl_add_u64 v[18:19], v[0:1], 0, s[68:69]
	ds_read_b128 v[4:7], v31
	ds_read_b128 v[0:3], v31 offset:16
	ds_read_b128 v[36:39], v31 offset:256
	ds_read_b128 v[40:43], v31 offset:272
	s_mov_b64 s[98:99], 0x2000
	v_lshl_add_u64 v[58:59], v[22:23], 2, s[26:27]
	v_lshl_add_u64 v[44:45], v[18:19], 0, v[8:9]
	global_load_dword v60, v[58:59], off
	global_load_dword v61, v[58:59], off offset:128
	global_load_dword v62, v[58:59], off offset:256
	global_load_dword v63, v[58:59], off offset:384
	v_lshl_add_u64 v[52:53], v[10:11], 0, s[98:99]
	v_lshl_add_u64 v[46:47], v[44:45], 0, s[98:99]
	v_lshl_add_u64 v[54:55], v[52:53], 0, s[98:99]
	v_lshl_add_u64 v[48:49], v[46:47], 0, s[98:99]
	v_lshl_add_u64 v[56:57], v[54:55], 0, s[98:99]
	v_lshl_add_u64 v[50:51], v[48:49], 0, s[98:99]
	global_load_dwordx4 v[68:71], v[10:11], off
	global_load_dwordx4 v[100:103], v[44:45], off
	global_load_dwordx4 v[76:79], v[52:53], off
	global_load_dwordx4 v[108:111], v[46:47], off
	global_load_dwordx4 v[84:87], v[54:55], off
	global_load_dwordx4 v[116:119], v[48:49], off
	global_load_dwordx4 v[92:95], v[56:57], off
	global_load_dwordx4 v[124:127], v[50:51], off
	global_load_dwordx4 v[72:75], v[10:11], off offset:128
	global_load_dwordx4 v[104:107], v[44:45], off offset:128
	global_load_dwordx4 v[80:83], v[52:53], off offset:128
	global_load_dwordx4 v[112:115], v[46:47], off offset:128
	global_load_dwordx4 v[88:91], v[54:55], off offset:128
	global_load_dwordx4 v[120:123], v[48:49], off offset:128
	global_load_dwordx4 v[96:99], v[56:57], off offset:128
	global_load_dwordx4 v[128:131], v[50:51], off offset:128
	v_lshl_or_b32 v16, v22, 7, v34
	v_add_u32_e32 v30, s60, v16
	v_bfe_u32 v64, v28, 4, 2
	v_and_b32_e32 v29, 15, v28
	s_movk_i32 s9, 0xffc0
	v_and_b32_e32 v65, 64, v28
	v_readlane_b32 s36, v254, 6
	v_readlane_b32 s46, v254, 16
	v_readlane_b32 s47, v254, 17
	s_mov_b64 s[24:25], s[46:47]
	v_lshlrev_b32_e32 v144, 1, v65
	v_readlane_b32 s37, v254, 7
	v_readlane_b32 s38, v254, 8
	v_readlane_b32 s39, v254, 9
	v_readlane_b32 s40, v254, 10
	v_readlane_b32 s41, v254, 11
	v_readlane_b32 s42, v254, 12
	v_readlane_b32 s43, v254, 13
	v_readlane_b32 s44, v254, 14
	v_readlane_b32 s45, v254, 15
	v_readlane_b32 s48, v254, 18
	v_readlane_b32 s49, v254, 19
	v_readlane_b32 s50, v254, 20
	v_readlane_b32 s51, v254, 21
	v_ashrrev_i32_e32 v132, 1, v28
	v_and_or_b32 v66, v132, s9, v29
	v_ashrrev_i32_e32 v67, 31, v66
	s_add_u32 s9, s24, s22
	s_addc_u32 s23, s25, s23
	s_add_u32 s22, s9, s3
	s_addc_u32 s23, s23, 0
	s_lshl_b32 s2, s2, 8
	s_add_u32 s2, s12, s2
	s_addc_u32 s3, s13, 0
	v_lshl_add_u64 v[132:133], s[2:3], 0, v[144:145]
	v_lshlrev_b32_e32 v144, 3, v64
	v_lshl_add_u64 v[146:147], v[66:67], 2, s[22:23]
	v_lshl_add_u64 v[132:133], v[132:133], 0, v[144:145]
	v_add_u32_e32 v134, s8, v66
	s_mov_b64 s[2:3], 0x71e0000
	v_ashrrev_i32_e32 v135, 31, v134
	v_lshl_add_u64 v[132:133], v[132:133], 0, s[2:3]
	v_lshlrev_b64 v[134:135], 10, v[134:135]
	s_mov_b64 s[98:99], 0x4000
	v_lshl_add_u64 v[216:217], v[132:133], 0, v[134:135]
	v_lshl_add_u64 v[218:219], v[216:217], 0, s[98:99]
	v_lshl_add_u64 v[220:221], v[218:219], 0, s[98:99]
	v_lshl_add_u64 v[222:223], v[220:221], 0, s[98:99]
	global_load_dword v186, v[146:147], off
	global_load_dword v188, v[146:147], off offset:64
	global_load_dword v206, v[146:147], off offset:128
	global_load_dword v208, v[146:147], off offset:192
	global_load_dwordx2 v[154:155], v[216:217], off
	global_load_dwordx2 v[156:157], v[216:217], off offset:32
	global_load_dwordx2 v[158:159], v[216:217], off offset:64
	global_load_dwordx2 v[160:161], v[216:217], off offset:96
	global_load_dwordx2 v[162:163], v[218:219], off
	global_load_dwordx2 v[164:165], v[218:219], off offset:32
	global_load_dwordx2 v[166:167], v[218:219], off offset:64
	global_load_dwordx2 v[168:169], v[218:219], off offset:96
	global_load_dwordx2 v[170:171], v[220:221], off
	global_load_dwordx2 v[172:173], v[220:221], off offset:32
	global_load_dwordx2 v[174:175], v[220:221], off offset:64
	global_load_dwordx2 v[176:177], v[220:221], off offset:96
	global_load_dwordx2 v[178:179], v[222:223], off
	global_load_dwordx2 v[180:181], v[222:223], off offset:32
	global_load_dwordx2 v[182:183], v[222:223], off offset:64
	global_load_dwordx2 v[184:185], v[222:223], off offset:96
	s_waitcnt vmcnt(34) lgkmcnt(0)
	ds_write_b128 v30, v[68:71]
	v_lshlrev_b32_e32 v132, 16, v100
	v_and_b32_e32 v133, 0xffff0000, v100
	v_mul_f32_e32 v132, v4, v132
	v_mul_f32_e32 v133, v5, v133
	v_mul_f32_e32 v132, v132, v60
	v_mul_f32_e32 v133, v133, v60
	v_cvt_pk_bf16_f32 v100, v132, v133
	v_lshlrev_b32_e32 v134, 16, v101
	v_and_b32_e32 v135, 0xffff0000, v101
	v_mul_f32_e32 v134, v6, v134
	v_mul_f32_e32 v135, v7, v135
	v_mul_f32_e32 v134, v134, v60
	v_mul_f32_e32 v135, v135, v60
	v_cvt_pk_bf16_f32 v101, v134, v135
	v_lshlrev_b32_e32 v132, 16, v102
	v_and_b32_e32 v133, 0xffff0000, v102
	v_mul_f32_e32 v132, v0, v132
	v_mul_f32_e32 v133, v1, v133
	v_mul_f32_e32 v132, v132, v60
	v_mul_f32_e32 v133, v133, v60
	v_cvt_pk_bf16_f32 v102, v132, v133
	v_lshlrev_b32_e32 v134, 16, v103
	v_and_b32_e32 v135, 0xffff0000, v103
	v_mul_f32_e32 v134, v2, v134
	v_mul_f32_e32 v135, v3, v135
	v_mul_f32_e32 v134, v134, v60
	v_mul_f32_e32 v135, v135, v60
	v_cvt_pk_bf16_f32 v103, v134, v135
	ds_write_b128 v30, v[100:103] offset:16384
	s_waitcnt vmcnt(32)
	ds_write_b128 v30, v[76:79] offset:4096
	v_lshlrev_b32_e32 v132, 16, v108
	v_and_b32_e32 v133, 0xffff0000, v108
	v_mul_f32_e32 v132, v4, v132
	v_mul_f32_e32 v133, v5, v133
	v_mul_f32_e32 v132, v132, v61
	v_mul_f32_e32 v133, v133, v61
	v_cvt_pk_bf16_f32 v108, v132, v133
	v_lshlrev_b32_e32 v134, 16, v109
	v_and_b32_e32 v135, 0xffff0000, v109
	v_mul_f32_e32 v134, v6, v134
	v_mul_f32_e32 v135, v7, v135
	v_mul_f32_e32 v134, v134, v61
	v_mul_f32_e32 v135, v135, v61
	v_cvt_pk_bf16_f32 v109, v134, v135
	v_lshlrev_b32_e32 v132, 16, v110
	v_and_b32_e32 v133, 0xffff0000, v110
	v_mul_f32_e32 v132, v0, v132
	v_mul_f32_e32 v133, v1, v133
	v_mul_f32_e32 v132, v132, v61
	v_mul_f32_e32 v133, v133, v61
	v_cvt_pk_bf16_f32 v110, v132, v133
	v_lshlrev_b32_e32 v134, 16, v111
	v_and_b32_e32 v135, 0xffff0000, v111
	v_mul_f32_e32 v134, v2, v134
	v_mul_f32_e32 v135, v3, v135
	v_mul_f32_e32 v134, v134, v61
	v_mul_f32_e32 v135, v135, v61
	v_cvt_pk_bf16_f32 v111, v134, v135
	ds_write_b128 v30, v[108:111] offset:20480
	s_waitcnt vmcnt(30)
	ds_write_b128 v30, v[84:87] offset:8192
	v_lshlrev_b32_e32 v132, 16, v116
	v_and_b32_e32 v133, 0xffff0000, v116
	v_mul_f32_e32 v132, v4, v132
	v_mul_f32_e32 v133, v5, v133
	v_mul_f32_e32 v132, v132, v62
	v_mul_f32_e32 v133, v133, v62
	v_cvt_pk_bf16_f32 v116, v132, v133
	v_lshlrev_b32_e32 v134, 16, v117
	v_and_b32_e32 v135, 0xffff0000, v117
	v_mul_f32_e32 v134, v6, v134
	v_mul_f32_e32 v135, v7, v135
	v_mul_f32_e32 v134, v134, v62
	v_mul_f32_e32 v135, v135, v62
	v_cvt_pk_bf16_f32 v117, v134, v135
	v_lshlrev_b32_e32 v132, 16, v118
	v_and_b32_e32 v133, 0xffff0000, v118
	v_mul_f32_e32 v132, v0, v132
	v_mul_f32_e32 v133, v1, v133
	v_mul_f32_e32 v132, v132, v62
	v_mul_f32_e32 v133, v133, v62
	v_cvt_pk_bf16_f32 v118, v132, v133
	v_lshlrev_b32_e32 v134, 16, v119
	v_and_b32_e32 v135, 0xffff0000, v119
	v_mul_f32_e32 v134, v2, v134
	v_mul_f32_e32 v135, v3, v135
	v_mul_f32_e32 v134, v134, v62
	v_mul_f32_e32 v135, v135, v62
	v_cvt_pk_bf16_f32 v119, v134, v135
	ds_write_b128 v30, v[116:119] offset:24576
	s_waitcnt vmcnt(28)
	ds_write_b128 v30, v[92:95] offset:12288
	v_lshlrev_b32_e32 v132, 16, v124
	v_and_b32_e32 v133, 0xffff0000, v124
	v_mul_f32_e32 v132, v4, v132
	v_mul_f32_e32 v133, v5, v133
	v_mul_f32_e32 v132, v132, v63
	v_mul_f32_e32 v133, v133, v63
	v_cvt_pk_bf16_f32 v124, v132, v133
	v_lshlrev_b32_e32 v134, 16, v125
	v_and_b32_e32 v135, 0xffff0000, v125
	v_mul_f32_e32 v134, v6, v134
	v_mul_f32_e32 v135, v7, v135
	v_mul_f32_e32 v134, v134, v63
	v_mul_f32_e32 v135, v135, v63
	v_cvt_pk_bf16_f32 v125, v134, v135
	v_lshlrev_b32_e32 v132, 16, v126
	v_and_b32_e32 v133, 0xffff0000, v126
	v_mul_f32_e32 v132, v0, v132
	v_mul_f32_e32 v133, v1, v133
	v_mul_f32_e32 v132, v132, v63
	v_mul_f32_e32 v133, v133, v63
	v_cvt_pk_bf16_f32 v126, v132, v133
	v_lshlrev_b32_e32 v134, 16, v127
	v_and_b32_e32 v135, 0xffff0000, v127
	v_mul_f32_e32 v134, v2, v134
	v_mul_f32_e32 v135, v3, v135
	v_mul_f32_e32 v134, v134, v63
	v_mul_f32_e32 v135, v135, v63
	v_cvt_pk_bf16_f32 v127, v134, v135
	ds_write_b128 v30, v[124:127] offset:28672
	s_waitcnt vmcnt(26)
	ds_write_b128 v30, v[72:75] offset:32768
	v_lshlrev_b32_e32 v132, 16, v104
	v_and_b32_e32 v133, 0xffff0000, v104
	v_mul_f32_e32 v132, v36, v132
	v_mul_f32_e32 v133, v37, v133
	v_mul_f32_e32 v132, v132, v60
	v_mul_f32_e32 v133, v133, v60
	v_cvt_pk_bf16_f32 v104, v132, v133
	v_lshlrev_b32_e32 v134, 16, v105
	v_and_b32_e32 v135, 0xffff0000, v105
	v_mul_f32_e32 v134, v38, v134
	v_mul_f32_e32 v135, v39, v135
	v_mul_f32_e32 v134, v134, v60
	v_mul_f32_e32 v135, v135, v60
	v_cvt_pk_bf16_f32 v105, v134, v135
	v_lshlrev_b32_e32 v132, 16, v106
	v_and_b32_e32 v133, 0xffff0000, v106
	v_mul_f32_e32 v132, v40, v132
	v_mul_f32_e32 v133, v41, v133
	v_mul_f32_e32 v132, v132, v60
	v_mul_f32_e32 v133, v133, v60
	v_cvt_pk_bf16_f32 v106, v132, v133
	v_lshlrev_b32_e32 v134, 16, v107
	v_and_b32_e32 v135, 0xffff0000, v107
	v_mul_f32_e32 v134, v42, v134
	v_mul_f32_e32 v135, v43, v135
	v_mul_f32_e32 v134, v134, v60
	v_mul_f32_e32 v135, v135, v60
	v_cvt_pk_bf16_f32 v107, v134, v135
	ds_write_b128 v30, v[104:107] offset:49152
	s_waitcnt vmcnt(24)
	ds_write_b128 v30, v[80:83] offset:36864
	v_lshlrev_b32_e32 v132, 16, v112
	v_and_b32_e32 v133, 0xffff0000, v112
	v_mul_f32_e32 v132, v36, v132
	v_mul_f32_e32 v133, v37, v133
	v_mul_f32_e32 v132, v132, v61
	v_mul_f32_e32 v133, v133, v61
	v_cvt_pk_bf16_f32 v112, v132, v133
	v_lshlrev_b32_e32 v134, 16, v113
	v_and_b32_e32 v135, 0xffff0000, v113
	v_mul_f32_e32 v134, v38, v134
	v_mul_f32_e32 v135, v39, v135
	v_mul_f32_e32 v134, v134, v61
	v_mul_f32_e32 v135, v135, v61
	v_cvt_pk_bf16_f32 v113, v134, v135
	v_lshlrev_b32_e32 v132, 16, v114
	v_and_b32_e32 v133, 0xffff0000, v114
	v_mul_f32_e32 v132, v40, v132
	v_mul_f32_e32 v133, v41, v133
	v_mul_f32_e32 v132, v132, v61
	v_mul_f32_e32 v133, v133, v61
	v_cvt_pk_bf16_f32 v114, v132, v133
	v_lshlrev_b32_e32 v134, 16, v115
	v_and_b32_e32 v135, 0xffff0000, v115
	v_mul_f32_e32 v134, v42, v134
	v_mul_f32_e32 v135, v43, v135
	v_mul_f32_e32 v134, v134, v61
	v_mul_f32_e32 v135, v135, v61
	v_cvt_pk_bf16_f32 v115, v134, v135
	ds_write_b128 v30, v[112:115] offset:53248
	s_waitcnt vmcnt(22)
	ds_write_b128 v30, v[88:91] offset:40960
	v_lshlrev_b32_e32 v132, 16, v120
	v_and_b32_e32 v133, 0xffff0000, v120
	v_mul_f32_e32 v132, v36, v132
	v_mul_f32_e32 v133, v37, v133
	v_mul_f32_e32 v132, v132, v62
	v_mul_f32_e32 v133, v133, v62
	v_cvt_pk_bf16_f32 v120, v132, v133
	v_lshlrev_b32_e32 v134, 16, v121
	v_and_b32_e32 v135, 0xffff0000, v121
	v_mul_f32_e32 v134, v38, v134
	v_mul_f32_e32 v135, v39, v135
	v_mul_f32_e32 v134, v134, v62
	v_mul_f32_e32 v135, v135, v62
	v_cvt_pk_bf16_f32 v121, v134, v135
	v_lshlrev_b32_e32 v132, 16, v122
	v_and_b32_e32 v133, 0xffff0000, v122
	v_mul_f32_e32 v132, v40, v132
	v_mul_f32_e32 v133, v41, v133
	v_mul_f32_e32 v132, v132, v62
	v_mul_f32_e32 v133, v133, v62
	v_cvt_pk_bf16_f32 v122, v132, v133
	v_lshlrev_b32_e32 v134, 16, v123
	v_and_b32_e32 v135, 0xffff0000, v123
	v_mul_f32_e32 v134, v42, v134
	v_mul_f32_e32 v135, v43, v135
	v_mul_f32_e32 v134, v134, v62
	v_mul_f32_e32 v135, v135, v62
	v_cvt_pk_bf16_f32 v123, v134, v135
	ds_write_b128 v30, v[120:123] offset:57344
	s_waitcnt vmcnt(20)
	ds_write_b128 v30, v[96:99] offset:45056
	v_lshlrev_b32_e32 v132, 16, v128
	v_and_b32_e32 v133, 0xffff0000, v128
	v_mul_f32_e32 v132, v36, v132
	v_mul_f32_e32 v133, v37, v133
	v_mul_f32_e32 v132, v132, v63
	v_mul_f32_e32 v133, v133, v63
	v_cvt_pk_bf16_f32 v128, v132, v133
	v_lshlrev_b32_e32 v134, 16, v129
	v_and_b32_e32 v135, 0xffff0000, v129
	v_mul_f32_e32 v134, v38, v134
	v_mul_f32_e32 v135, v39, v135
	v_mul_f32_e32 v134, v134, v63
	v_mul_f32_e32 v135, v135, v63
	v_cvt_pk_bf16_f32 v129, v134, v135
	v_lshlrev_b32_e32 v132, 16, v130
	v_and_b32_e32 v133, 0xffff0000, v130
	v_mul_f32_e32 v132, v40, v132
	v_mul_f32_e32 v133, v41, v133
	v_mul_f32_e32 v132, v132, v63
	v_mul_f32_e32 v133, v133, v63
	v_cvt_pk_bf16_f32 v130, v132, v133
	v_lshlrev_b32_e32 v134, 16, v131
	v_and_b32_e32 v135, 0xffff0000, v131
	v_mul_f32_e32 v134, v42, v134
	v_mul_f32_e32 v135, v43, v135
	v_mul_f32_e32 v134, v134, v63
	v_mul_f32_e32 v135, v135, v63
	v_cvt_pk_bf16_f32 v131, v134, v135
	ds_write_b128 v30, v[128:131] offset:61440
	v_lshrrev_b32_e32 v1, 1, v28
	v_bfe_u32 v2, v28, 1, 3
	v_bitop3_b32 v1, v1, v64, 7 bitop3:0x6c
	v_bitop3_b32 v2, v64, v2, 4 bitop3:0x36
	v_lshlrev_b32_e32 v0, 7, v66
	v_lshlrev_b32_e32 v1, 4, v1
	v_lshlrev_b32_e32 v2, 4, v2
	v_or_b32_e32 v3, v1, v0
	v_or_b32_e32 v67, v2, v0
	v_lshlrev_b32_e32 v0, 7, v28
	v_and_b32_e32 v0, 0x2780, v0
	v_or_b32_e32 v16, v1, v0
	v_add_u32_e32 v100, s60, v3
	v_add_u32_e32 v101, s60, v16
	s_waitcnt lgkmcnt(0)
	s_barrier
	v_or_b32_e32 v84, v2, v0
	ds_read_b128 v[0:3], v100
	ds_read_b128 v[4:7], v100 offset:2048
	ds_read_b128 v[8:11], v100 offset:4096
	ds_read_b128 v[12:15], v100 offset:6144
	ds_read_b128 v[16:19], v101 offset:16384
	ds_read_b128 v[20:23], v101 offset:18432
	ds_read_b128 v[24:27], v101 offset:20480
	ds_read_b128 v[28:31], v101 offset:22528
	v_add_u32_e32 v67, s60, v67
	v_add_u32_e32 v124, s60, v84
	s_waitcnt lgkmcnt(3)
	v_mfma_f32_16x16x32_bf16 v[32:35], v[16:19], v[0:3], 0
	s_waitcnt lgkmcnt(2)
	v_mfma_f32_16x16x32_bf16 v[36:39], v[20:23], v[0:3], 0
	s_waitcnt lgkmcnt(1)
	v_mfma_f32_16x16x32_bf16 v[40:43], v[24:27], v[0:3], 0
	s_waitcnt lgkmcnt(0)
	v_mfma_f32_16x16x32_bf16 v[0:3], v[28:31], v[0:3], 0
	v_mfma_f32_16x16x32_bf16 v[44:47], v[16:19], v[4:7], 0
	v_mfma_f32_16x16x32_bf16 v[48:51], v[20:23], v[4:7], 0
	v_mfma_f32_16x16x32_bf16 v[52:55], v[24:27], v[4:7], 0
	v_mfma_f32_16x16x32_bf16 v[4:7], v[28:31], v[4:7], 0
	v_mfma_f32_16x16x32_bf16 v[56:59], v[16:19], v[8:11], 0
	v_mfma_f32_16x16x32_bf16 v[60:63], v[20:23], v[8:11], 0
	v_mfma_f32_16x16x32_bf16 v[68:71], v[24:27], v[8:11], 0
	v_mfma_f32_16x16x32_bf16 v[8:11], v[28:31], v[8:11], 0
	v_mfma_f32_16x16x32_bf16 v[16:19], v[16:19], v[12:15], 0
	v_mfma_f32_16x16x32_bf16 v[20:23], v[20:23], v[12:15], 0
	v_mfma_f32_16x16x32_bf16 v[24:27], v[24:27], v[12:15], 0
	v_mfma_f32_16x16x32_bf16 v[12:15], v[28:31], v[12:15], 0
	ds_read_b128 v[28:31], v67
	ds_read_b128 v[72:75], v67 offset:2048
	ds_read_b128 v[76:79], v67 offset:4096
	ds_read_b128 v[80:83], v67 offset:6144
	ds_read_b128 v[84:87], v124 offset:16384
	ds_read_b128 v[88:91], v124 offset:18432
	ds_read_b128 v[92:95], v124 offset:20480
	ds_read_b128 v[96:99], v124 offset:22528
	s_waitcnt lgkmcnt(3)
	v_mfma_f32_16x16x32_bf16 v[32:35], v[84:87], v[28:31], v[32:35]
	s_waitcnt lgkmcnt(2)
	v_mfma_f32_16x16x32_bf16 v[36:39], v[88:91], v[28:31], v[36:39]
	s_waitcnt lgkmcnt(1)
	v_mfma_f32_16x16x32_bf16 v[40:43], v[92:95], v[28:31], v[40:43]
	s_waitcnt lgkmcnt(0)
	v_mfma_f32_16x16x32_bf16 v[0:3], v[96:99], v[28:31], v[0:3]
	v_mfma_f32_16x16x32_bf16 v[28:31], v[84:87], v[72:75], v[44:47]
	v_mfma_f32_16x16x32_bf16 v[44:47], v[88:91], v[72:75], v[48:51]
	v_mfma_f32_16x16x32_bf16 v[48:51], v[92:95], v[72:75], v[52:55]
	v_mfma_f32_16x16x32_bf16 v[4:7], v[96:99], v[72:75], v[4:7]
	v_mfma_f32_16x16x32_bf16 v[52:55], v[84:87], v[76:79], v[56:59]
	v_mfma_f32_16x16x32_bf16 v[56:59], v[88:91], v[76:79], v[60:63]
	v_mfma_f32_16x16x32_bf16 v[60:63], v[92:95], v[76:79], v[68:71]
	v_mfma_f32_16x16x32_bf16 v[8:11], v[96:99], v[76:79], v[8:11]
	v_mfma_f32_16x16x32_bf16 v[16:19], v[84:87], v[80:83], v[16:19]
	v_mfma_f32_16x16x32_bf16 v[20:23], v[88:91], v[80:83], v[20:23]
	v_mfma_f32_16x16x32_bf16 v[24:27], v[92:95], v[80:83], v[24:27]
	v_mfma_f32_16x16x32_bf16 v[12:15], v[96:99], v[80:83], v[12:15]
	ds_read_b128 v[68:71], v100 offset:32768
	ds_read_b128 v[72:75], v100 offset:34816
	ds_read_b128 v[76:79], v100 offset:36864
	ds_read_b128 v[80:83], v100 offset:38912
	ds_read_b128 v[84:87], v101 offset:49152
	ds_read_b128 v[88:91], v101 offset:51200
	ds_read_b128 v[92:95], v101 offset:53248
	ds_read_b128 v[96:99], v101 offset:55296
	s_waitcnt lgkmcnt(3)
	v_mfma_f32_16x16x32_bf16 v[32:35], v[84:87], v[68:71], v[32:35]
	s_waitcnt lgkmcnt(2)
	v_mfma_f32_16x16x32_bf16 v[36:39], v[88:91], v[68:71], v[36:39]
	s_waitcnt lgkmcnt(1)
	v_mfma_f32_16x16x32_bf16 v[40:43], v[92:95], v[68:71], v[40:43]
	s_waitcnt lgkmcnt(0)
	v_mfma_f32_16x16x32_bf16 v[0:3], v[96:99], v[68:71], v[0:3]
	v_mfma_f32_16x16x32_bf16 v[28:31], v[84:87], v[72:75], v[28:31]
	v_mfma_f32_16x16x32_bf16 v[68:71], v[88:91], v[72:75], v[44:47]
	v_mfma_f32_16x16x32_bf16 v[100:103], v[92:95], v[72:75], v[48:51]
	v_mfma_f32_16x16x32_bf16 v[4:7], v[96:99], v[72:75], v[4:7]
	v_mfma_f32_16x16x32_bf16 v[72:75], v[84:87], v[76:79], v[52:55]
	v_mfma_f32_16x16x32_bf16 v[104:107], v[88:91], v[76:79], v[56:59]
	v_mfma_f32_16x16x32_bf16 v[108:111], v[92:95], v[76:79], v[60:63]
	v_mfma_f32_16x16x32_bf16 v[8:11], v[96:99], v[76:79], v[8:11]
	v_mfma_f32_16x16x32_bf16 v[76:79], v[84:87], v[80:83], v[16:19]
	v_mfma_f32_16x16x32_bf16 v[84:87], v[88:91], v[80:83], v[20:23]
	v_mfma_f32_16x16x32_bf16 v[88:91], v[92:95], v[80:83], v[24:27]
	v_mfma_f32_16x16x32_bf16 v[80:83], v[96:99], v[80:83], v[12:15]
	s_nop 2
	ds_read_b128 v[12:15], v67 offset:32768
	ds_read_b128 v[16:19], v67 offset:34816
	ds_read_b128 v[92:95], v67 offset:36864
	ds_read_b128 v[96:99], v67 offset:38912
	ds_read_b128 v[112:115], v124 offset:49152
	ds_read_b128 v[116:119], v124 offset:51200
	ds_read_b128 v[120:123], v124 offset:53248
	ds_read_b128 v[124:127], v124 offset:55296
	s_waitcnt lgkmcnt(0)
	v_mfma_f32_16x16x32_bf16 v[32:35], v[112:115], v[12:15], v[32:35]
	v_mfma_f32_16x16x32_bf16 v[36:39], v[116:119], v[12:15], v[36:39]
	v_mfma_f32_16x16x32_bf16 v[40:43], v[120:123], v[12:15], v[40:43]
	v_mfma_f32_16x16x32_bf16 v[0:3], v[124:127], v[12:15], v[0:3]
	v_mfma_f32_16x16x32_bf16 v[28:31], v[112:115], v[16:19], v[28:31]
	v_mfma_f32_16x16x32_bf16 v[68:71], v[116:119], v[16:19], v[68:71]
	v_mfma_f32_16x16x32_bf16 v[100:103], v[120:123], v[16:19], v[100:103]
	v_mfma_f32_16x16x32_bf16 v[4:7], v[124:127], v[16:19], v[4:7]
	v_mfma_f32_16x16x32_bf16 v[72:75], v[112:115], v[92:95], v[72:75]
	v_mfma_f32_16x16x32_bf16 v[104:107], v[116:119], v[92:95], v[104:107]
	v_mfma_f32_16x16x32_bf16 v[108:111], v[120:123], v[92:95], v[108:111]
	v_mfma_f32_16x16x32_bf16 v[8:11], v[124:127], v[92:95], v[8:11]
	v_mfma_f32_16x16x32_bf16 v[76:79], v[112:115], v[96:99], v[76:79]
	v_mfma_f32_16x16x32_bf16 v[84:87], v[116:119], v[96:99], v[84:87]
	v_mfma_f32_16x16x32_bf16 v[88:91], v[120:123], v[96:99], v[88:91]
	v_mfma_f32_16x16x32_bf16 v[80:83], v[124:127], v[96:99], v[80:83]
	s_waitcnt vmcnt(15)
	v_pk_add_f32 v[32:33], v[32:33], v[186:187] op_sel_hi:[1,0]
	v_pk_add_f32 v[34:35], v[34:35], v[186:187] op_sel_hi:[1,0]
	v_lshlrev_b32_e32 v132, 16, v154
	v_and_b32_e32 v133, 0xffff0000, v154
	v_lshlrev_b32_e32 v134, 16, v155
	v_and_b32_e32 v135, 0xffff0000, v155
	v_pk_mul_f32 v[32:33], v[32:33], v[132:133]
	v_pk_mul_f32 v[34:35], v[34:35], v[134:135]
	v_cvt_pk_bf16_f32 v154, v32, v33
	v_cvt_pk_bf16_f32 v155, v34, v35
	global_store_dwordx2 v[216:217], v[154:155], off
	s_waitcnt vmcnt(15)
	v_pk_add_f32 v[36:37], v[36:37], v[186:187] op_sel_hi:[1,0]
	v_pk_add_f32 v[38:39], v[38:39], v[186:187] op_sel_hi:[1,0]
	v_lshlrev_b32_e32 v132, 16, v156
	v_and_b32_e32 v133, 0xffff0000, v156
	v_lshlrev_b32_e32 v134, 16, v157
	v_and_b32_e32 v135, 0xffff0000, v157
	v_pk_mul_f32 v[36:37], v[36:37], v[132:133]
	v_pk_mul_f32 v[38:39], v[38:39], v[134:135]
	v_cvt_pk_bf16_f32 v156, v36, v37
	v_cvt_pk_bf16_f32 v157, v38, v39
	global_store_dwordx2 v[216:217], v[156:157], off offset:32
	s_waitcnt vmcnt(15)
	v_pk_add_f32 v[40:41], v[40:41], v[186:187] op_sel_hi:[1,0]
	v_pk_add_f32 v[42:43], v[42:43], v[186:187] op_sel_hi:[1,0]
	v_lshlrev_b32_e32 v132, 16, v158
	v_and_b32_e32 v133, 0xffff0000, v158
	v_lshlrev_b32_e32 v134, 16, v159
	v_and_b32_e32 v135, 0xffff0000, v159
	v_pk_mul_f32 v[40:41], v[40:41], v[132:133]
	v_pk_mul_f32 v[42:43], v[42:43], v[134:135]
	v_cvt_pk_bf16_f32 v158, v40, v41
	v_cvt_pk_bf16_f32 v159, v42, v43
	global_store_dwordx2 v[216:217], v[158:159], off offset:64
	s_waitcnt vmcnt(15)
	v_pk_add_f32 v[0:1], v[0:1], v[186:187] op_sel_hi:[1,0]
	v_pk_add_f32 v[2:3], v[2:3], v[186:187] op_sel_hi:[1,0]
	v_lshlrev_b32_e32 v132, 16, v160
	v_and_b32_e32 v133, 0xffff0000, v160
	v_lshlrev_b32_e32 v134, 16, v161
	v_and_b32_e32 v135, 0xffff0000, v161
	v_pk_mul_f32 v[0:1], v[0:1], v[132:133]
	v_pk_mul_f32 v[2:3], v[2:3], v[134:135]
	v_cvt_pk_bf16_f32 v160, v0, v1
	v_cvt_pk_bf16_f32 v161, v2, v3
	global_store_dwordx2 v[216:217], v[160:161], off offset:96
	s_waitcnt vmcnt(15)
	v_pk_add_f32 v[28:29], v[28:29], v[188:189] op_sel_hi:[1,0]
	v_pk_add_f32 v[30:31], v[30:31], v[188:189] op_sel_hi:[1,0]
	v_lshlrev_b32_e32 v132, 16, v162
	v_and_b32_e32 v133, 0xffff0000, v162
	v_lshlrev_b32_e32 v134, 16, v163
	v_and_b32_e32 v135, 0xffff0000, v163
	v_pk_mul_f32 v[28:29], v[28:29], v[132:133]
	v_pk_mul_f32 v[30:31], v[30:31], v[134:135]
	v_cvt_pk_bf16_f32 v162, v28, v29
	v_cvt_pk_bf16_f32 v163, v30, v31
	global_store_dwordx2 v[218:219], v[162:163], off
	s_waitcnt vmcnt(15)
	v_pk_add_f32 v[68:69], v[68:69], v[188:189] op_sel_hi:[1,0]
	v_pk_add_f32 v[70:71], v[70:71], v[188:189] op_sel_hi:[1,0]
	v_lshlrev_b32_e32 v132, 16, v164
	v_and_b32_e32 v133, 0xffff0000, v164
	v_lshlrev_b32_e32 v134, 16, v165
	v_and_b32_e32 v135, 0xffff0000, v165
	v_pk_mul_f32 v[68:69], v[68:69], v[132:133]
	v_pk_mul_f32 v[70:71], v[70:71], v[134:135]
	v_cvt_pk_bf16_f32 v164, v68, v69
	v_cvt_pk_bf16_f32 v165, v70, v71
	global_store_dwordx2 v[218:219], v[164:165], off offset:32
	s_waitcnt vmcnt(15)
	v_pk_add_f32 v[100:101], v[100:101], v[188:189] op_sel_hi:[1,0]
	v_pk_add_f32 v[102:103], v[102:103], v[188:189] op_sel_hi:[1,0]
	v_lshlrev_b32_e32 v132, 16, v166
	v_and_b32_e32 v133, 0xffff0000, v166
	v_lshlrev_b32_e32 v134, 16, v167
	v_and_b32_e32 v135, 0xffff0000, v167
	v_pk_mul_f32 v[100:101], v[100:101], v[132:133]
	v_pk_mul_f32 v[102:103], v[102:103], v[134:135]
	v_cvt_pk_bf16_f32 v166, v100, v101
	v_cvt_pk_bf16_f32 v167, v102, v103
	global_store_dwordx2 v[218:219], v[166:167], off offset:64
	s_waitcnt vmcnt(15)
	v_pk_add_f32 v[4:5], v[4:5], v[188:189] op_sel_hi:[1,0]
	v_pk_add_f32 v[6:7], v[6:7], v[188:189] op_sel_hi:[1,0]
	v_lshlrev_b32_e32 v132, 16, v168
	v_and_b32_e32 v133, 0xffff0000, v168
	v_lshlrev_b32_e32 v134, 16, v169
	v_and_b32_e32 v135, 0xffff0000, v169
	v_pk_mul_f32 v[4:5], v[4:5], v[132:133]
	v_pk_mul_f32 v[6:7], v[6:7], v[134:135]
	v_cvt_pk_bf16_f32 v168, v4, v5
	v_cvt_pk_bf16_f32 v169, v6, v7
	global_store_dwordx2 v[218:219], v[168:169], off offset:96
	s_waitcnt vmcnt(15)
	v_pk_add_f32 v[72:73], v[72:73], v[206:207] op_sel_hi:[1,0]
	v_pk_add_f32 v[74:75], v[74:75], v[206:207] op_sel_hi:[1,0]
	v_lshlrev_b32_e32 v132, 16, v170
	v_and_b32_e32 v133, 0xffff0000, v170
	v_lshlrev_b32_e32 v134, 16, v171
	v_and_b32_e32 v135, 0xffff0000, v171
	v_pk_mul_f32 v[72:73], v[72:73], v[132:133]
	v_pk_mul_f32 v[74:75], v[74:75], v[134:135]
	v_cvt_pk_bf16_f32 v170, v72, v73
	v_cvt_pk_bf16_f32 v171, v74, v75
	global_store_dwordx2 v[220:221], v[170:171], off
	s_waitcnt vmcnt(15)
	v_pk_add_f32 v[104:105], v[104:105], v[206:207] op_sel_hi:[1,0]
	v_pk_add_f32 v[106:107], v[106:107], v[206:207] op_sel_hi:[1,0]
	v_lshlrev_b32_e32 v132, 16, v172
	v_and_b32_e32 v133, 0xffff0000, v172
	v_lshlrev_b32_e32 v134, 16, v173
	v_and_b32_e32 v135, 0xffff0000, v173
	v_pk_mul_f32 v[104:105], v[104:105], v[132:133]
	v_pk_mul_f32 v[106:107], v[106:107], v[134:135]
	v_cvt_pk_bf16_f32 v172, v104, v105
	v_cvt_pk_bf16_f32 v173, v106, v107
	global_store_dwordx2 v[220:221], v[172:173], off offset:32
	s_waitcnt vmcnt(15)
	v_pk_add_f32 v[108:109], v[108:109], v[206:207] op_sel_hi:[1,0]
	v_pk_add_f32 v[110:111], v[110:111], v[206:207] op_sel_hi:[1,0]
	v_lshlrev_b32_e32 v132, 16, v174
	v_and_b32_e32 v133, 0xffff0000, v174
	v_lshlrev_b32_e32 v134, 16, v175
	v_and_b32_e32 v135, 0xffff0000, v175
	v_pk_mul_f32 v[108:109], v[108:109], v[132:133]
	v_pk_mul_f32 v[110:111], v[110:111], v[134:135]
	v_cvt_pk_bf16_f32 v174, v108, v109
	v_cvt_pk_bf16_f32 v175, v110, v111
	global_store_dwordx2 v[220:221], v[174:175], off offset:64
	s_waitcnt vmcnt(15)
	v_pk_add_f32 v[8:9], v[8:9], v[206:207] op_sel_hi:[1,0]
	v_pk_add_f32 v[10:11], v[10:11], v[206:207] op_sel_hi:[1,0]
	v_lshlrev_b32_e32 v132, 16, v176
	v_and_b32_e32 v133, 0xffff0000, v176
	v_lshlrev_b32_e32 v134, 16, v177
	v_and_b32_e32 v135, 0xffff0000, v177
	v_pk_mul_f32 v[8:9], v[8:9], v[132:133]
	v_pk_mul_f32 v[10:11], v[10:11], v[134:135]
	v_cvt_pk_bf16_f32 v176, v8, v9
	v_cvt_pk_bf16_f32 v177, v10, v11
	global_store_dwordx2 v[220:221], v[176:177], off offset:96
	s_waitcnt vmcnt(15)
	v_pk_add_f32 v[76:77], v[76:77], v[208:209] op_sel_hi:[1,0]
	v_pk_add_f32 v[78:79], v[78:79], v[208:209] op_sel_hi:[1,0]
	v_lshlrev_b32_e32 v132, 16, v178
	v_and_b32_e32 v133, 0xffff0000, v178
	v_lshlrev_b32_e32 v134, 16, v179
	v_and_b32_e32 v135, 0xffff0000, v179
	v_pk_mul_f32 v[76:77], v[76:77], v[132:133]
	v_pk_mul_f32 v[78:79], v[78:79], v[134:135]
	v_cvt_pk_bf16_f32 v178, v76, v77
	v_cvt_pk_bf16_f32 v179, v78, v79
	global_store_dwordx2 v[222:223], v[178:179], off
	s_waitcnt vmcnt(15)
	v_pk_add_f32 v[84:85], v[84:85], v[208:209] op_sel_hi:[1,0]
	v_pk_add_f32 v[86:87], v[86:87], v[208:209] op_sel_hi:[1,0]
	v_lshlrev_b32_e32 v132, 16, v180
	v_and_b32_e32 v133, 0xffff0000, v180
	v_lshlrev_b32_e32 v134, 16, v181
	v_and_b32_e32 v135, 0xffff0000, v181
	v_pk_mul_f32 v[84:85], v[84:85], v[132:133]
	v_pk_mul_f32 v[86:87], v[86:87], v[134:135]
	v_cvt_pk_bf16_f32 v180, v84, v85
	v_cvt_pk_bf16_f32 v181, v86, v87
	global_store_dwordx2 v[222:223], v[180:181], off offset:32
	s_waitcnt vmcnt(15)
	v_pk_add_f32 v[88:89], v[88:89], v[208:209] op_sel_hi:[1,0]
	v_pk_add_f32 v[90:91], v[90:91], v[208:209] op_sel_hi:[1,0]
	v_lshlrev_b32_e32 v132, 16, v182
	v_and_b32_e32 v133, 0xffff0000, v182
	v_lshlrev_b32_e32 v134, 16, v183
	v_and_b32_e32 v135, 0xffff0000, v183
	v_pk_mul_f32 v[88:89], v[88:89], v[132:133]
	v_pk_mul_f32 v[90:91], v[90:91], v[134:135]
	v_cvt_pk_bf16_f32 v182, v88, v89
	v_cvt_pk_bf16_f32 v183, v90, v91
	global_store_dwordx2 v[222:223], v[182:183], off offset:64
	s_waitcnt vmcnt(15)
	v_pk_add_f32 v[80:81], v[80:81], v[208:209] op_sel_hi:[1,0]
	v_pk_add_f32 v[82:83], v[82:83], v[208:209] op_sel_hi:[1,0]
	v_lshlrev_b32_e32 v132, 16, v184
	v_and_b32_e32 v133, 0xffff0000, v184
	v_lshlrev_b32_e32 v134, 16, v185
	v_and_b32_e32 v135, 0xffff0000, v185
	v_pk_mul_f32 v[80:81], v[80:81], v[132:133]
	v_pk_mul_f32 v[82:83], v[82:83], v[134:135]
	v_cvt_pk_bf16_f32 v184, v80, v81
	v_cvt_pk_bf16_f32 v185, v82, v83
	global_store_dwordx2 v[222:223], v[184:185], off offset:96
	s_add_i32 s0, s0, s70
	s_cmpk_lt_i32 s0, 0x200
	s_cbranch_scc0 .LBB0_380
.LBB0_378:
	v_readlane_b32 s36, v254, 6
	s_waitcnt lgkmcnt(0)
	v_mov_b32_e32 v28, v191
	v_mov_b32_e32 v0, v191
	s_ashr_i32 s24, s0, 2
	v_readlane_b32 s42, v254, 12
	v_readlane_b32 s43, v254, 13
	s_movk_i32 s9, 0x80
	s_lshl_b32 s8, s24, 7
	s_mov_b64 s[12:13], s[74:75]
	s_mov_b64 s[2:3], s[74:75]
	s_mov_b64 s[26:27], s[42:43]
	v_cmp_gt_i32_e32 vcc, s9, v0
	v_readlane_b32 s37, v254, 7
	v_readlane_b32 s38, v254, 8
	v_readlane_b32 s39, v254, 9
	v_readlane_b32 s40, v254, 10
	v_readlane_b32 s41, v254, 11
	v_readlane_b32 s44, v254, 14
	v_readlane_b32 s45, v254, 15
	v_readlane_b32 s46, v254, 16
	v_readlane_b32 s47, v254, 17
	v_readlane_b32 s48, v254, 18
	v_readlane_b32 s49, v254, 19
	v_readlane_b32 s50, v254, 20
	v_readlane_b32 s51, v254, 21
	s_barrier
	s_and_saveexec_b64 s[22:23], vcc
	s_cbranch_execz .LBB0_377
	s_add_u32 s25, s2, s29
	s_addc_u32 s31, s3, s30
	s_ashr_i32 s9, s8, 31
	s_lshl_b64 s[2:3], s[8:9], 2
	s_add_u32 s2, s25, s2
	s_addc_u32 s3, s31, s3
	v_ashrrev_i32_e32 v1, 31, v0
	v_lshl_add_u64 v[2:3], v[0:1], 2, s[2:3]
	s_mov_b32 s2, 0x117e0000
	v_add_co_u32_e32 v4, vcc, s2, v2
	s_mov_b64 s[98:99], 0x10000
	s_nop 1
	v_addc_co_u32_e32 v5, vcc, 0, v3, vcc
	v_lshl_add_u64 v[6:7], v[4:5], 0, s[98:99]
	v_lshl_add_u64 v[8:9], v[6:7], 0, s[98:99]
	v_lshl_add_u64 v[10:11], v[8:9], 0, s[98:99]
	v_lshl_add_u64 v[12:13], v[10:11], 0, s[98:99]
	v_lshl_add_u64 v[14:15], v[12:13], 0, s[98:99]
	v_lshl_add_u64 v[16:17], v[14:15], 0, s[98:99]
	v_lshl_add_u64 v[18:19], v[16:17], 0, s[98:99]
	global_load_dword v20, v[4:5], off
	global_load_dword v21, v[6:7], off
	global_load_dword v22, v[8:9], off
	global_load_dword v23, v[10:11], off
	global_load_dword v24, v[12:13], off
	global_load_dword v25, v[14:15], off
	global_load_dword v26, v[16:17], off
	global_load_dword v27, v[18:19], off
	s_waitcnt vmcnt(0)
	v_add_f32_e32 v1, 0, v20
	v_add_f32_e32 v1, v1, v21
	v_add_f32_e32 v1, v1, v22
	v_add_f32_e32 v1, v1, v23
	v_add_f32_e32 v1, v1, v24
	v_add_f32_e32 v1, v1, v25
	v_add_f32_e32 v1, v1, v26
	v_add_f32_e32 v1, v1, v27
	v_fmamk_f32 v1, v1, 0x3b000000, v192
	v_cmp_gt_f32_e32 vcc, s58, v1
	v_mul_f32_e32 v2, 0x4b800000, v1
	s_nop 0
	v_cndmask_b32_e32 v1, v1, v2, vcc
	v_rsq_f32_e32 v1, v1
	s_nop 0
	v_mul_f32_e32 v2, 0x45800000, v1
	v_cndmask_b32_e32 v1, v1, v2, vcc
	v_lshl_add_u32 v2, v0, 2, s28
	ds_write_b32 v2, v1
	s_branch .LBB0_377
